# v20 with the static second attention item paired blk7->blk5 / blk6->blk4 (second ticket = bid) to stagger the two groups' third-round pops
# baseline (speedup 1.0000x reference)
; __device__ __forceinline__ void phase_attn(const Params& p, LAS unsigned char* lds, unsigned* queue) {
;     ...
;     for (;;) {
;         if (tid == 0) *tick = __hip_atomic_fetch_add(queue, 1u, __ATOMIC_RELAXED, __HIP_MEMORY_SCOPE_AGENT);
;         __syncthreads();
;         const int idx = (int)*tick;
;         if (idx >= 512) break;
;         const int blk = 7 - (idx >> 6), bh = idx & 63, b = bh >> 3, h = bh & 7;
.Lq_try2:
	s_cmp_eq_u32 s98, 2
	s_cbranch_scc0 .Lq_dyn
	s_mov_b32 s0, s2
	v_mov_b32_e32 v251, 0
	v_mov_b32_e32 v4, s0
	s_branch .LBB0_336
